# v14 + sample-scan tasks redistributed: scan workgroups take 40 of 64, others 8 each
# baseline (speedup 1.0000x reference)
.LBB0_1177:
.LBB0_1178:
	s_lshr_b32 s28, s82, 2
	s_lshl_b32 s28, s28, 6
	s_and_b32 s44, s82, 3
	s_lshl_b32 s44, s44, 3
	s_add_i32 s44, s44, 32
	s_and_b32 s25, s82, 3
	s_cselect_b32 s44, s44, 0
	s_cselect_b32 s25, 8, 40
	s_add_i32 s28, s28, s44
